# v7 + P9 phase (c) hand-written: top-16 merge on 16 lanes per token across all 8 waves (was wave 0 only)
# speedup vs baseline: 1.0120x; 1.0120x over previous
; #define LAS __attribute__((address_space(3)))
; __device__ __forceinline__ void peer_score_unit(const Frame& F, int l, int unit) {
;     ...
;     for (int repc = 0; repc < P9_REP_C; ++repc) if (tid < 64) {
;         float a[16], c[16]; int p[16];
;         const LAS float* bl = SV + (64 + tid) * 16;
;         const float b0v = bl[0];
; #pragma unroll
;         for (int i = 0; i < 16; ++i) { a[i] = SV[tid * 16 + i]; c[i] = a[i] + b0v; p[i] = 0; }
;         float fv[16]; int fi[16];
; #pragma unroll
;         for (int k = 0; k < 16; ++k) {
;             float best = c[0]; int bi = 0;
; #pragma unroll
;             for (int i = 1; i < 16; ++i) if (c[i] > best) { best = c[i]; bi = i; }
;             int pj = 0, lim = 16;
; #pragma unroll
;             for (int i = 0; i < 16; ++i) { pj = (i == bi) ? p[i] : pj; lim = (i == bi) ? 16 / (i + 1) : lim; }
;             fv[k] = best; fi[k] = bi * 16 + pj;
;             const int np = pj + 1; const float nb = bl[np & 15];
; #pragma unroll
;             for (int i = 0; i < 16; ++i) if (i == bi) { p[i] = np; c[i] = (np < lim) ? a[i] + nb : -INFINITY; }
;         }
.LBB0_2049:
	s_or_b64 exec, exec, s[0:1]
	v_cmp_gt_i32_e32 vcc, 64, v50
	s_waitcnt lgkmcnt(0)
	s_barrier
	s_mov_b32 s12, 0x1112347f
	s_mov_b32 s13, 0
	s_mov_b32 s20, 0x10001
	v_and_b32_e32 v26, 15, v50
	v_lshlrev_b32_e32 v27, 2, v26
	v_lshl_add_u32 v22, v50, 2, s58
	v_lshrrev_b64 v[28:29], v27, s[12:13]
	v_and_b32_e32 v23, -64, v22
	ds_read_b32 v2, v22
	ds_read_b32 v12, v22 offset:2048
	ds_read_b32 v3, v23 offset:4096
	ds_read_b32 v13, v23 offset:6144
	v_lshlrev_b32_e32 v1, 8, v26
	v_and_b32_e32 v28, 15, v28
	v_lshlrev_b32_e32 v30, 3, v50
	v_lshl_add_u32 v7, v28, 2, v1
	v_mov_b32_e32 v0, 0xff800000
	v_sub_u32_e32 v10, v23, v1
	v_add_u32_e32 v7, 4, v7
	v_and_b32_e32 v11, 0xffffff80, v30
	v_mov_b32_e32 v5, v1
	v_mov_b32_e32 v15, v1
	s_lshl_b32 s0, s7, 9
	s_lshl_b32 s1, s6, 6
	s_add_u32 s0, s0, s1
	s_add_u32 s8, s4, s0
	s_addc_u32 s9, s5, 0
	s_add_u32 s8, s8, 0x4a0d0000
	s_addc_u32 s9, s9, 0
	s_add_u32 s14, s8, 0x500000
	s_addc_u32 s15, s9, 0
	s_waitcnt lgkmcnt(0)
	v_add_f32_e32 v6, v2, v3
	v_add_f32_e32 v16, v12, v13
	v_cmp_lt_u32_e32 vcc, v5, v7
	v_cmp_lt_u32_e64 s[10:11], v15, v7
	s_nop 0
	v_cndmask_b32_e32 v4, v0, v6, vcc
	v_cndmask_b32_e64 v14, v0, v16, s[10:11]
	s_nop 0
	v_max_f32_dpp v24, v4, v4 row_ror:8 row_mask:0xf bank_mask:0xf
	v_max_f32_dpp v25, v14, v14 row_ror:8 row_mask:0xf bank_mask:0xf
	s_nop 0
	v_max_f32_dpp v24, v24, v24 row_ror:4 row_mask:0xf bank_mask:0xf
	v_max_f32_dpp v25, v25, v25 row_ror:4 row_mask:0xf bank_mask:0xf
	s_nop 0
	v_max_f32_dpp v24, v24, v24 row_ror:2 row_mask:0xf bank_mask:0xf
	v_max_f32_dpp v25, v25, v25 row_ror:2 row_mask:0xf bank_mask:0xf
	s_nop 0
	v_max_f32_dpp v24, v24, v24 row_ror:1 row_mask:0xf bank_mask:0xf
	v_max_f32_dpp v25, v25, v25 row_ror:1 row_mask:0xf bank_mask:0xf
	v_cmp_eq_f32_e32 vcc, v4, v24
	v_cmp_eq_f32_e64 s[10:11], v14, v25
	s_sub_u32 s0, vcc_lo, s20
	s_subb_u32 s1, vcc_hi, s20
	s_andn2_b64 exec, vcc, s[0:1]
	ds_write_b64 v11, v[4:5] offset:0
	v_add_u32_e32 v5, 4, v5
	v_add_u32_e32 v9, v10, v5
	ds_read_b32 v3, v9 offset:4096
	s_sub_u32 s0, s10, s20
	s_subb_u32 s1, s11, s20
	s_andn2_b64 exec, s[10:11], s[0:1]
	ds_write_b64 v11, v[14:15] offset:4096
	v_add_u32_e32 v15, 4, v15
	v_add_u32_e32 v19, v10, v15
	ds_read_b32 v13, v19 offset:6144
	s_mov_b64 exec, -1
	s_waitcnt lgkmcnt(0)
	v_add_f32_e32 v6, v2, v3
	v_add_f32_e32 v16, v12, v13
	v_cmp_lt_u32_e32 vcc, v5, v7
	v_cmp_lt_u32_e64 s[10:11], v15, v7
	s_nop 0
	v_cndmask_b32_e32 v4, v0, v6, vcc
	v_cndmask_b32_e64 v14, v0, v16, s[10:11]
	s_nop 0
	v_max_f32_dpp v8, v4, v4 row_ror:8 row_mask:0xf bank_mask:0xf
	v_max_f32_dpp v18, v14, v14 row_ror:8 row_mask:0xf bank_mask:0xf
	s_nop 0
	v_max_f32_dpp v8, v8, v8 row_ror:4 row_mask:0xf bank_mask:0xf
	v_max_f32_dpp v18, v18, v18 row_ror:4 row_mask:0xf bank_mask:0xf
	s_nop 0
	v_max_f32_dpp v8, v8, v8 row_ror:2 row_mask:0xf bank_mask:0xf
	v_max_f32_dpp v18, v18, v18 row_ror:2 row_mask:0xf bank_mask:0xf
	s_nop 0
	v_max_f32_dpp v8, v8, v8 row_ror:1 row_mask:0xf bank_mask:0xf
	v_max_f32_dpp v18, v18, v18 row_ror:1 row_mask:0xf bank_mask:0xf
	v_cmp_eq_f32_e32 vcc, v4, v8
	v_cmp_eq_f32_e64 s[10:11], v14, v18
	s_sub_u32 s0, vcc_lo, s20
	s_subb_u32 s1, vcc_hi, s20
	s_andn2_b64 exec, vcc, s[0:1]
	ds_write_b64 v11, v[4:5] offset:8
	v_add_u32_e32 v5, 4, v5
	v_add_u32_e32 v9, v10, v5
	ds_read_b32 v3, v9 offset:4096
	s_sub_u32 s0, s10, s20
	s_subb_u32 s1, s11, s20
	s_andn2_b64 exec, s[10:11], s[0:1]
	ds_write_b64 v11, v[14:15] offset:4104
	v_add_u32_e32 v15, 4, v15
	v_add_u32_e32 v19, v10, v15
	ds_read_b32 v13, v19 offset:6144
	s_mov_b64 exec, -1
	s_waitcnt lgkmcnt(0)
	v_add_f32_e32 v6, v2, v3
	v_add_f32_e32 v16, v12, v13
	v_cmp_lt_u32_e32 vcc, v5, v7
	v_cmp_lt_u32_e64 s[10:11], v15, v7
	s_nop 0
	v_cndmask_b32_e32 v4, v0, v6, vcc
	v_cndmask_b32_e64 v14, v0, v16, s[10:11]
	s_nop 0
	v_max_f32_dpp v8, v4, v4 row_ror:8 row_mask:0xf bank_mask:0xf
	v_max_f32_dpp v18, v14, v14 row_ror:8 row_mask:0xf bank_mask:0xf
	s_nop 0
	v_max_f32_dpp v8, v8, v8 row_ror:4 row_mask:0xf bank_mask:0xf
	v_max_f32_dpp v18, v18, v18 row_ror:4 row_mask:0xf bank_mask:0xf
	s_nop 0
	v_max_f32_dpp v8, v8, v8 row_ror:2 row_mask:0xf bank_mask:0xf
	v_max_f32_dpp v18, v18, v18 row_ror:2 row_mask:0xf bank_mask:0xf
	s_nop 0
	v_max_f32_dpp v8, v8, v8 row_ror:1 row_mask:0xf bank_mask:0xf
	v_max_f32_dpp v18, v18, v18 row_ror:1 row_mask:0xf bank_mask:0xf
	v_cmp_eq_f32_e32 vcc, v4, v8
	v_cmp_eq_f32_e64 s[10:11], v14, v18
	s_sub_u32 s0, vcc_lo, s20
	s_subb_u32 s1, vcc_hi, s20
	s_andn2_b64 exec, vcc, s[0:1]
	ds_write_b64 v11, v[4:5] offset:16
	v_add_u32_e32 v5, 4, v5
	v_add_u32_e32 v9, v10, v5
	ds_read_b32 v3, v9 offset:4096
	s_sub_u32 s0, s10, s20
	s_subb_u32 s1, s11, s20
	s_andn2_b64 exec, s[10:11], s[0:1]
	ds_write_b64 v11, v[14:15] offset:4112
	v_add_u32_e32 v15, 4, v15
	v_add_u32_e32 v19, v10, v15
	ds_read_b32 v13, v19 offset:6144
	s_mov_b64 exec, -1
	s_waitcnt lgkmcnt(0)
	v_add_f32_e32 v6, v2, v3
	v_add_f32_e32 v16, v12, v13
	v_cmp_lt_u32_e32 vcc, v5, v7
	v_cmp_lt_u32_e64 s[10:11], v15, v7
	s_nop 0
	v_cndmask_b32_e32 v4, v0, v6, vcc
	v_cndmask_b32_e64 v14, v0, v16, s[10:11]
	s_nop 0
	v_max_f32_dpp v8, v4, v4 row_ror:8 row_mask:0xf bank_mask:0xf
	v_max_f32_dpp v18, v14, v14 row_ror:8 row_mask:0xf bank_mask:0xf
	s_nop 0
	v_max_f32_dpp v8, v8, v8 row_ror:4 row_mask:0xf bank_mask:0xf
	v_max_f32_dpp v18, v18, v18 row_ror:4 row_mask:0xf bank_mask:0xf
	s_nop 0
	v_max_f32_dpp v8, v8, v8 row_ror:2 row_mask:0xf bank_mask:0xf
	v_max_f32_dpp v18, v18, v18 row_ror:2 row_mask:0xf bank_mask:0xf
	s_nop 0
	v_max_f32_dpp v8, v8, v8 row_ror:1 row_mask:0xf bank_mask:0xf
	v_max_f32_dpp v18, v18, v18 row_ror:1 row_mask:0xf bank_mask:0xf
	v_cmp_eq_f32_e32 vcc, v4, v8
	v_cmp_eq_f32_e64 s[10:11], v14, v18
	s_sub_u32 s0, vcc_lo, s20
	s_subb_u32 s1, vcc_hi, s20
	s_andn2_b64 exec, vcc, s[0:1]
	ds_write_b64 v11, v[4:5] offset:24
	v_add_u32_e32 v5, 4, v5
	v_add_u32_e32 v9, v10, v5
	ds_read_b32 v3, v9 offset:4096
	s_sub_u32 s0, s10, s20
	s_subb_u32 s1, s11, s20
	s_andn2_b64 exec, s[10:11], s[0:1]
	ds_write_b64 v11, v[14:15] offset:4120
	v_add_u32_e32 v15, 4, v15
	v_add_u32_e32 v19, v10, v15
	ds_read_b32 v13, v19 offset:6144
	s_mov_b64 exec, -1
	s_waitcnt lgkmcnt(0)
; __device__ __forceinline__ void peer_score_unit(const Frame& F, int l, int unit) {
;     ...
;         for (int k = 0; k < 16; ++k) {
;             float best = c[0]; int bi = 0;
; #pragma unroll
;             for (int i = 1; i < 16; ++i) if (c[i] > best) { best = c[i]; bi = i; }
;             int pj = 0, lim = 16;
; #pragma unroll
;             for (int i = 0; i < 16; ++i) { pj = (i == bi) ? p[i] : pj; lim = (i == bi) ? 16 / (i + 1) : lim; }
;             fv[k] = best; fi[k] = bi * 16 + pj;
;             const int np = pj + 1; const float nb = bl[np & 15];
; #pragma unroll
;             for (int i = 0; i < 16; ++i) if (i == bi) { p[i] = np; c[i] = (np < lim) ? a[i] + nb : -INFINITY; }
;         }
	v_add_f32_e32 v6, v2, v3
	v_add_f32_e32 v16, v12, v13
	v_cmp_lt_u32_e32 vcc, v5, v7
	v_cmp_lt_u32_e64 s[10:11], v15, v7
	s_nop 0
	v_cndmask_b32_e32 v4, v0, v6, vcc
	v_cndmask_b32_e64 v14, v0, v16, s[10:11]
	s_nop 0
	v_max_f32_dpp v8, v4, v4 row_ror:8 row_mask:0xf bank_mask:0xf
	v_max_f32_dpp v18, v14, v14 row_ror:8 row_mask:0xf bank_mask:0xf
	s_nop 0
	v_max_f32_dpp v8, v8, v8 row_ror:4 row_mask:0xf bank_mask:0xf
	v_max_f32_dpp v18, v18, v18 row_ror:4 row_mask:0xf bank_mask:0xf
	s_nop 0
	v_max_f32_dpp v8, v8, v8 row_ror:2 row_mask:0xf bank_mask:0xf
	v_max_f32_dpp v18, v18, v18 row_ror:2 row_mask:0xf bank_mask:0xf
	s_nop 0
	v_max_f32_dpp v8, v8, v8 row_ror:1 row_mask:0xf bank_mask:0xf
	v_max_f32_dpp v18, v18, v18 row_ror:1 row_mask:0xf bank_mask:0xf
	v_cmp_eq_f32_e32 vcc, v4, v8
	v_cmp_eq_f32_e64 s[10:11], v14, v18
	s_sub_u32 s0, vcc_lo, s20
	s_subb_u32 s1, vcc_hi, s20
	s_andn2_b64 exec, vcc, s[0:1]
	ds_write_b64 v11, v[4:5] offset:32
	v_add_u32_e32 v5, 4, v5
	v_add_u32_e32 v9, v10, v5
	ds_read_b32 v3, v9 offset:4096
	s_sub_u32 s0, s10, s20
	s_subb_u32 s1, s11, s20
	s_andn2_b64 exec, s[10:11], s[0:1]
	ds_write_b64 v11, v[14:15] offset:4128
	v_add_u32_e32 v15, 4, v15
	v_add_u32_e32 v19, v10, v15
	ds_read_b32 v13, v19 offset:6144
	s_mov_b64 exec, -1
	s_waitcnt lgkmcnt(0)
	v_add_f32_e32 v6, v2, v3
	v_add_f32_e32 v16, v12, v13
	v_cmp_lt_u32_e32 vcc, v5, v7
	v_cmp_lt_u32_e64 s[10:11], v15, v7
	s_nop 0
	v_cndmask_b32_e32 v4, v0, v6, vcc
	v_cndmask_b32_e64 v14, v0, v16, s[10:11]
	s_nop 0
	v_max_f32_dpp v8, v4, v4 row_ror:8 row_mask:0xf bank_mask:0xf
	v_max_f32_dpp v18, v14, v14 row_ror:8 row_mask:0xf bank_mask:0xf
	s_nop 0
	v_max_f32_dpp v8, v8, v8 row_ror:4 row_mask:0xf bank_mask:0xf
	v_max_f32_dpp v18, v18, v18 row_ror:4 row_mask:0xf bank_mask:0xf
	s_nop 0
	v_max_f32_dpp v8, v8, v8 row_ror:2 row_mask:0xf bank_mask:0xf
	v_max_f32_dpp v18, v18, v18 row_ror:2 row_mask:0xf bank_mask:0xf
	s_nop 0
	v_max_f32_dpp v8, v8, v8 row_ror:1 row_mask:0xf bank_mask:0xf
	v_max_f32_dpp v18, v18, v18 row_ror:1 row_mask:0xf bank_mask:0xf
	v_cmp_eq_f32_e32 vcc, v4, v8
	v_cmp_eq_f32_e64 s[10:11], v14, v18
	s_sub_u32 s0, vcc_lo, s20
	s_subb_u32 s1, vcc_hi, s20
	s_andn2_b64 exec, vcc, s[0:1]
	ds_write_b64 v11, v[4:5] offset:40
	v_add_u32_e32 v5, 4, v5
	v_add_u32_e32 v9, v10, v5
	ds_read_b32 v3, v9 offset:4096
	s_sub_u32 s0, s10, s20
	s_subb_u32 s1, s11, s20
	s_andn2_b64 exec, s[10:11], s[0:1]
	ds_write_b64 v11, v[14:15] offset:4136
	v_add_u32_e32 v15, 4, v15
	v_add_u32_e32 v19, v10, v15
	ds_read_b32 v13, v19 offset:6144
	s_mov_b64 exec, -1
	s_waitcnt lgkmcnt(0)
	v_add_f32_e32 v6, v2, v3
	v_add_f32_e32 v16, v12, v13
	v_cmp_lt_u32_e32 vcc, v5, v7
	v_cmp_lt_u32_e64 s[10:11], v15, v7
	s_nop 0
	v_cndmask_b32_e32 v4, v0, v6, vcc
	v_cndmask_b32_e64 v14, v0, v16, s[10:11]
	s_nop 0
	v_max_f32_dpp v8, v4, v4 row_ror:8 row_mask:0xf bank_mask:0xf
	v_max_f32_dpp v18, v14, v14 row_ror:8 row_mask:0xf bank_mask:0xf
	s_nop 0
	v_max_f32_dpp v8, v8, v8 row_ror:4 row_mask:0xf bank_mask:0xf
	v_max_f32_dpp v18, v18, v18 row_ror:4 row_mask:0xf bank_mask:0xf
	s_nop 0
	v_max_f32_dpp v8, v8, v8 row_ror:2 row_mask:0xf bank_mask:0xf
	v_max_f32_dpp v18, v18, v18 row_ror:2 row_mask:0xf bank_mask:0xf
	s_nop 0
	v_max_f32_dpp v8, v8, v8 row_ror:1 row_mask:0xf bank_mask:0xf
	v_max_f32_dpp v18, v18, v18 row_ror:1 row_mask:0xf bank_mask:0xf
	v_cmp_eq_f32_e32 vcc, v4, v8
	v_cmp_eq_f32_e64 s[10:11], v14, v18
	s_sub_u32 s0, vcc_lo, s20
	s_subb_u32 s1, vcc_hi, s20
	s_andn2_b64 exec, vcc, s[0:1]
	ds_write_b64 v11, v[4:5] offset:48
	v_add_u32_e32 v5, 4, v5
	v_add_u32_e32 v9, v10, v5
	ds_read_b32 v3, v9 offset:4096
	s_sub_u32 s0, s10, s20
	s_subb_u32 s1, s11, s20
	s_andn2_b64 exec, s[10:11], s[0:1]
	ds_write_b64 v11, v[14:15] offset:4144
	v_add_u32_e32 v15, 4, v15
	v_add_u32_e32 v19, v10, v15
	ds_read_b32 v13, v19 offset:6144
	s_mov_b64 exec, -1
	s_waitcnt lgkmcnt(0)
	v_add_f32_e32 v6, v2, v3
	v_add_f32_e32 v16, v12, v13
	v_cmp_lt_u32_e32 vcc, v5, v7
	v_cmp_lt_u32_e64 s[10:11], v15, v7
	s_nop 0
	v_cndmask_b32_e32 v4, v0, v6, vcc
	v_cndmask_b32_e64 v14, v0, v16, s[10:11]
	s_nop 0
	v_max_f32_dpp v8, v4, v4 row_ror:8 row_mask:0xf bank_mask:0xf
	v_max_f32_dpp v18, v14, v14 row_ror:8 row_mask:0xf bank_mask:0xf
	s_nop 0
	v_max_f32_dpp v8, v8, v8 row_ror:4 row_mask:0xf bank_mask:0xf
	v_max_f32_dpp v18, v18, v18 row_ror:4 row_mask:0xf bank_mask:0xf
	s_nop 0
	v_max_f32_dpp v8, v8, v8 row_ror:2 row_mask:0xf bank_mask:0xf
	v_max_f32_dpp v18, v18, v18 row_ror:2 row_mask:0xf bank_mask:0xf
	s_nop 0
	v_max_f32_dpp v8, v8, v8 row_ror:1 row_mask:0xf bank_mask:0xf
	v_max_f32_dpp v18, v18, v18 row_ror:1 row_mask:0xf bank_mask:0xf
	v_cmp_eq_f32_e32 vcc, v4, v8
	v_cmp_eq_f32_e64 s[10:11], v14, v18
	s_sub_u32 s0, vcc_lo, s20
	s_subb_u32 s1, vcc_hi, s20
	s_andn2_b64 exec, vcc, s[0:1]
	ds_write_b64 v11, v[4:5] offset:56
	v_add_u32_e32 v5, 4, v5
	v_add_u32_e32 v9, v10, v5
	ds_read_b32 v3, v9 offset:4096
	s_sub_u32 s0, s10, s20
	s_subb_u32 s1, s11, s20
	s_andn2_b64 exec, s[10:11], s[0:1]
	ds_write_b64 v11, v[14:15] offset:4152
	v_add_u32_e32 v15, 4, v15
	v_add_u32_e32 v19, v10, v15
	ds_read_b32 v13, v19 offset:6144
	s_mov_b64 exec, -1
	s_waitcnt lgkmcnt(0)
; __device__ __forceinline__ void peer_score_unit(const Frame& F, int l, int unit) {
;     ...
; #pragma unroll
;         for (int k = 0; k < 16; ++k) {
;             float best = c[0]; int bi = 0;
; #pragma unroll
;             for (int i = 1; i < 16; ++i) if (c[i] > best) { best = c[i]; bi = i; }
;             int pj = 0, lim = 16;
; #pragma unroll
;             for (int i = 0; i < 16; ++i) { pj = (i == bi) ? p[i] : pj; lim = (i == bi) ? 16 / (i + 1) : lim; }
;             fv[k] = best; fi[k] = bi * 16 + pj;
;             const int np = pj + 1; const float nb = bl[np & 15];
; #pragma unroll
;             for (int i = 0; i < 16; ++i) if (i == bi) { p[i] = np; c[i] = (np < lim) ? a[i] + nb : -INFINITY; }
;         }
	v_add_f32_e32 v6, v2, v3
	v_add_f32_e32 v16, v12, v13
	v_cmp_lt_u32_e32 vcc, v5, v7
	v_cmp_lt_u32_e64 s[10:11], v15, v7
	s_nop 0
	v_cndmask_b32_e32 v4, v0, v6, vcc
	v_cndmask_b32_e64 v14, v0, v16, s[10:11]
	s_nop 0
	v_max_f32_dpp v8, v4, v4 row_ror:8 row_mask:0xf bank_mask:0xf
	v_max_f32_dpp v18, v14, v14 row_ror:8 row_mask:0xf bank_mask:0xf
	s_nop 0
	v_max_f32_dpp v8, v8, v8 row_ror:4 row_mask:0xf bank_mask:0xf
	v_max_f32_dpp v18, v18, v18 row_ror:4 row_mask:0xf bank_mask:0xf
	s_nop 0
	v_max_f32_dpp v8, v8, v8 row_ror:2 row_mask:0xf bank_mask:0xf
	v_max_f32_dpp v18, v18, v18 row_ror:2 row_mask:0xf bank_mask:0xf
	s_nop 0
	v_max_f32_dpp v8, v8, v8 row_ror:1 row_mask:0xf bank_mask:0xf
	v_max_f32_dpp v18, v18, v18 row_ror:1 row_mask:0xf bank_mask:0xf
	v_cmp_eq_f32_e32 vcc, v4, v8
	v_cmp_eq_f32_e64 s[10:11], v14, v18
	s_sub_u32 s0, vcc_lo, s20
	s_subb_u32 s1, vcc_hi, s20
	s_andn2_b64 exec, vcc, s[0:1]
	ds_write_b64 v11, v[4:5] offset:64
	v_add_u32_e32 v5, 4, v5
	v_add_u32_e32 v9, v10, v5
	ds_read_b32 v3, v9 offset:4096
	s_sub_u32 s0, s10, s20
	s_subb_u32 s1, s11, s20
	s_andn2_b64 exec, s[10:11], s[0:1]
	ds_write_b64 v11, v[14:15] offset:4160
	v_add_u32_e32 v15, 4, v15
	v_add_u32_e32 v19, v10, v15
	ds_read_b32 v13, v19 offset:6144
	s_mov_b64 exec, -1
	s_waitcnt lgkmcnt(0)
	v_add_f32_e32 v6, v2, v3
	v_add_f32_e32 v16, v12, v13
	v_cmp_lt_u32_e32 vcc, v5, v7
	v_cmp_lt_u32_e64 s[10:11], v15, v7
	s_nop 0
	v_cndmask_b32_e32 v4, v0, v6, vcc
	v_cndmask_b32_e64 v14, v0, v16, s[10:11]
	s_nop 0
	v_max_f32_dpp v8, v4, v4 row_ror:8 row_mask:0xf bank_mask:0xf
	v_max_f32_dpp v18, v14, v14 row_ror:8 row_mask:0xf bank_mask:0xf
	s_nop 0
	v_max_f32_dpp v8, v8, v8 row_ror:4 row_mask:0xf bank_mask:0xf
	v_max_f32_dpp v18, v18, v18 row_ror:4 row_mask:0xf bank_mask:0xf
	s_nop 0
	v_max_f32_dpp v8, v8, v8 row_ror:2 row_mask:0xf bank_mask:0xf
	v_max_f32_dpp v18, v18, v18 row_ror:2 row_mask:0xf bank_mask:0xf
	s_nop 0
	v_max_f32_dpp v8, v8, v8 row_ror:1 row_mask:0xf bank_mask:0xf
	v_max_f32_dpp v18, v18, v18 row_ror:1 row_mask:0xf bank_mask:0xf
	v_cmp_eq_f32_e32 vcc, v4, v8
	v_cmp_eq_f32_e64 s[10:11], v14, v18
	s_sub_u32 s0, vcc_lo, s20
	s_subb_u32 s1, vcc_hi, s20
	s_andn2_b64 exec, vcc, s[0:1]
	ds_write_b64 v11, v[4:5] offset:72
	v_add_u32_e32 v5, 4, v5
	v_add_u32_e32 v9, v10, v5
	ds_read_b32 v3, v9 offset:4096
	s_sub_u32 s0, s10, s20
	s_subb_u32 s1, s11, s20
	s_andn2_b64 exec, s[10:11], s[0:1]
	ds_write_b64 v11, v[14:15] offset:4168
	v_add_u32_e32 v15, 4, v15
	v_add_u32_e32 v19, v10, v15
	ds_read_b32 v13, v19 offset:6144
	s_mov_b64 exec, -1
	s_waitcnt lgkmcnt(0)
	v_add_f32_e32 v6, v2, v3
	v_add_f32_e32 v16, v12, v13
	v_cmp_lt_u32_e32 vcc, v5, v7
	v_cmp_lt_u32_e64 s[10:11], v15, v7
	s_nop 0
	v_cndmask_b32_e32 v4, v0, v6, vcc
	v_cndmask_b32_e64 v14, v0, v16, s[10:11]
	s_nop 0
	v_max_f32_dpp v8, v4, v4 row_ror:8 row_mask:0xf bank_mask:0xf
	v_max_f32_dpp v18, v14, v14 row_ror:8 row_mask:0xf bank_mask:0xf
	s_nop 0
	v_max_f32_dpp v8, v8, v8 row_ror:4 row_mask:0xf bank_mask:0xf
	v_max_f32_dpp v18, v18, v18 row_ror:4 row_mask:0xf bank_mask:0xf
	s_nop 0
	v_max_f32_dpp v8, v8, v8 row_ror:2 row_mask:0xf bank_mask:0xf
	v_max_f32_dpp v18, v18, v18 row_ror:2 row_mask:0xf bank_mask:0xf
	s_nop 0
	v_max_f32_dpp v8, v8, v8 row_ror:1 row_mask:0xf bank_mask:0xf
	v_max_f32_dpp v18, v18, v18 row_ror:1 row_mask:0xf bank_mask:0xf
	v_cmp_eq_f32_e32 vcc, v4, v8
	v_cmp_eq_f32_e64 s[10:11], v14, v18
	s_sub_u32 s0, vcc_lo, s20
	s_subb_u32 s1, vcc_hi, s20
	s_andn2_b64 exec, vcc, s[0:1]
	ds_write_b64 v11, v[4:5] offset:80
	v_add_u32_e32 v5, 4, v5
	v_add_u32_e32 v9, v10, v5
	ds_read_b32 v3, v9 offset:4096
	s_sub_u32 s0, s10, s20
	s_subb_u32 s1, s11, s20
	s_andn2_b64 exec, s[10:11], s[0:1]
	ds_write_b64 v11, v[14:15] offset:4176
	v_add_u32_e32 v15, 4, v15
	v_add_u32_e32 v19, v10, v15
	ds_read_b32 v13, v19 offset:6144
	s_mov_b64 exec, -1
	s_waitcnt lgkmcnt(0)
	v_add_f32_e32 v6, v2, v3
	v_add_f32_e32 v16, v12, v13
	v_cmp_lt_u32_e32 vcc, v5, v7
	v_cmp_lt_u32_e64 s[10:11], v15, v7
	s_nop 0
	v_cndmask_b32_e32 v4, v0, v6, vcc
	v_cndmask_b32_e64 v14, v0, v16, s[10:11]
	s_nop 0
	v_max_f32_dpp v8, v4, v4 row_ror:8 row_mask:0xf bank_mask:0xf
	v_max_f32_dpp v18, v14, v14 row_ror:8 row_mask:0xf bank_mask:0xf
	s_nop 0
	v_max_f32_dpp v8, v8, v8 row_ror:4 row_mask:0xf bank_mask:0xf
	v_max_f32_dpp v18, v18, v18 row_ror:4 row_mask:0xf bank_mask:0xf
	s_nop 0
	v_max_f32_dpp v8, v8, v8 row_ror:2 row_mask:0xf bank_mask:0xf
	v_max_f32_dpp v18, v18, v18 row_ror:2 row_mask:0xf bank_mask:0xf
	s_nop 0
	v_max_f32_dpp v8, v8, v8 row_ror:1 row_mask:0xf bank_mask:0xf
	v_max_f32_dpp v18, v18, v18 row_ror:1 row_mask:0xf bank_mask:0xf
	v_cmp_eq_f32_e32 vcc, v4, v8
	v_cmp_eq_f32_e64 s[10:11], v14, v18
	s_sub_u32 s0, vcc_lo, s20
	s_subb_u32 s1, vcc_hi, s20
	s_andn2_b64 exec, vcc, s[0:1]
	ds_write_b64 v11, v[4:5] offset:88
	v_add_u32_e32 v5, 4, v5
	v_add_u32_e32 v9, v10, v5
	ds_read_b32 v3, v9 offset:4096
	s_sub_u32 s0, s10, s20
	s_subb_u32 s1, s11, s20
	s_andn2_b64 exec, s[10:11], s[0:1]
	ds_write_b64 v11, v[14:15] offset:4184
	v_add_u32_e32 v15, 4, v15
	v_add_u32_e32 v19, v10, v15
	ds_read_b32 v13, v19 offset:6144
	s_mov_b64 exec, -1
	s_waitcnt lgkmcnt(0)
; __device__ __forceinline__ void peer_score_unit(const Frame& F, int l, int unit) {
;     ...
; #pragma unroll
;         for (int k = 0; k < 16; ++k) {
;             float best = c[0]; int bi = 0;
; #pragma unroll
;             for (int i = 1; i < 16; ++i) if (c[i] > best) { best = c[i]; bi = i; }
;             int pj = 0, lim = 16;
; #pragma unroll
;             for (int i = 0; i < 16; ++i) { pj = (i == bi) ? p[i] : pj; lim = (i == bi) ? 16 / (i + 1) : lim; }
;             fv[k] = best; fi[k] = bi * 16 + pj;
;             const int np = pj + 1; const float nb = bl[np & 15];
; #pragma unroll
;             for (int i = 0; i < 16; ++i) if (i == bi) { p[i] = np; c[i] = (np < lim) ? a[i] + nb : -INFINITY; }
;         }
	v_add_f32_e32 v6, v2, v3
	v_add_f32_e32 v16, v12, v13
	v_cmp_lt_u32_e32 vcc, v5, v7
	v_cmp_lt_u32_e64 s[10:11], v15, v7
	s_nop 0
	v_cndmask_b32_e32 v4, v0, v6, vcc
	v_cndmask_b32_e64 v14, v0, v16, s[10:11]
	s_nop 0
	v_max_f32_dpp v8, v4, v4 row_ror:8 row_mask:0xf bank_mask:0xf
	v_max_f32_dpp v18, v14, v14 row_ror:8 row_mask:0xf bank_mask:0xf
	s_nop 0
	v_max_f32_dpp v8, v8, v8 row_ror:4 row_mask:0xf bank_mask:0xf
	v_max_f32_dpp v18, v18, v18 row_ror:4 row_mask:0xf bank_mask:0xf
	s_nop 0
	v_max_f32_dpp v8, v8, v8 row_ror:2 row_mask:0xf bank_mask:0xf
	v_max_f32_dpp v18, v18, v18 row_ror:2 row_mask:0xf bank_mask:0xf
	s_nop 0
	v_max_f32_dpp v8, v8, v8 row_ror:1 row_mask:0xf bank_mask:0xf
	v_max_f32_dpp v18, v18, v18 row_ror:1 row_mask:0xf bank_mask:0xf
	v_cmp_eq_f32_e32 vcc, v4, v8
	v_cmp_eq_f32_e64 s[10:11], v14, v18
	s_sub_u32 s0, vcc_lo, s20
	s_subb_u32 s1, vcc_hi, s20
	s_andn2_b64 exec, vcc, s[0:1]
	ds_write_b64 v11, v[4:5] offset:96
	v_add_u32_e32 v5, 4, v5
	v_add_u32_e32 v9, v10, v5
	ds_read_b32 v3, v9 offset:4096
	s_sub_u32 s0, s10, s20
	s_subb_u32 s1, s11, s20
	s_andn2_b64 exec, s[10:11], s[0:1]
	ds_write_b64 v11, v[14:15] offset:4192
	v_add_u32_e32 v15, 4, v15
	v_add_u32_e32 v19, v10, v15
	ds_read_b32 v13, v19 offset:6144
	s_mov_b64 exec, -1
	s_waitcnt lgkmcnt(0)
	v_add_f32_e32 v6, v2, v3
	v_add_f32_e32 v16, v12, v13
	v_cmp_lt_u32_e32 vcc, v5, v7
	v_cmp_lt_u32_e64 s[10:11], v15, v7
	s_nop 0
	v_cndmask_b32_e32 v4, v0, v6, vcc
	v_cndmask_b32_e64 v14, v0, v16, s[10:11]
	s_nop 0
	v_max_f32_dpp v8, v4, v4 row_ror:8 row_mask:0xf bank_mask:0xf
	v_max_f32_dpp v18, v14, v14 row_ror:8 row_mask:0xf bank_mask:0xf
	s_nop 0
	v_max_f32_dpp v8, v8, v8 row_ror:4 row_mask:0xf bank_mask:0xf
	v_max_f32_dpp v18, v18, v18 row_ror:4 row_mask:0xf bank_mask:0xf
	s_nop 0
	v_max_f32_dpp v8, v8, v8 row_ror:2 row_mask:0xf bank_mask:0xf
	v_max_f32_dpp v18, v18, v18 row_ror:2 row_mask:0xf bank_mask:0xf
	s_nop 0
	v_max_f32_dpp v8, v8, v8 row_ror:1 row_mask:0xf bank_mask:0xf
	v_max_f32_dpp v18, v18, v18 row_ror:1 row_mask:0xf bank_mask:0xf
	v_cmp_eq_f32_e32 vcc, v4, v8
	v_cmp_eq_f32_e64 s[10:11], v14, v18
	s_sub_u32 s0, vcc_lo, s20
	s_subb_u32 s1, vcc_hi, s20
	s_andn2_b64 exec, vcc, s[0:1]
	ds_write_b64 v11, v[4:5] offset:104
	v_add_u32_e32 v5, 4, v5
	v_add_u32_e32 v9, v10, v5
	ds_read_b32 v3, v9 offset:4096
	s_sub_u32 s0, s10, s20
	s_subb_u32 s1, s11, s20
	s_andn2_b64 exec, s[10:11], s[0:1]
	ds_write_b64 v11, v[14:15] offset:4200
	v_add_u32_e32 v15, 4, v15
	v_add_u32_e32 v19, v10, v15
	ds_read_b32 v13, v19 offset:6144
	s_mov_b64 exec, -1
	s_waitcnt lgkmcnt(0)
	v_add_f32_e32 v6, v2, v3
	v_add_f32_e32 v16, v12, v13
	v_cmp_lt_u32_e32 vcc, v5, v7
	v_cmp_lt_u32_e64 s[10:11], v15, v7
	s_nop 0
	v_cndmask_b32_e32 v4, v0, v6, vcc
	v_cndmask_b32_e64 v14, v0, v16, s[10:11]
	s_nop 0
	v_max_f32_dpp v8, v4, v4 row_ror:8 row_mask:0xf bank_mask:0xf
	v_max_f32_dpp v18, v14, v14 row_ror:8 row_mask:0xf bank_mask:0xf
	s_nop 0
	v_max_f32_dpp v8, v8, v8 row_ror:4 row_mask:0xf bank_mask:0xf
	v_max_f32_dpp v18, v18, v18 row_ror:4 row_mask:0xf bank_mask:0xf
	s_nop 0
	v_max_f32_dpp v8, v8, v8 row_ror:2 row_mask:0xf bank_mask:0xf
	v_max_f32_dpp v18, v18, v18 row_ror:2 row_mask:0xf bank_mask:0xf
	s_nop 0
	v_max_f32_dpp v8, v8, v8 row_ror:1 row_mask:0xf bank_mask:0xf
	v_max_f32_dpp v18, v18, v18 row_ror:1 row_mask:0xf bank_mask:0xf
	v_cmp_eq_f32_e32 vcc, v4, v8
	v_cmp_eq_f32_e64 s[10:11], v14, v18
	s_sub_u32 s0, vcc_lo, s20
	s_subb_u32 s1, vcc_hi, s20
	s_andn2_b64 exec, vcc, s[0:1]
	ds_write_b64 v11, v[4:5] offset:112
	v_add_u32_e32 v5, 4, v5
	v_add_u32_e32 v9, v10, v5
	ds_read_b32 v3, v9 offset:4096
	s_sub_u32 s0, s10, s20
	s_subb_u32 s1, s11, s20
	s_andn2_b64 exec, s[10:11], s[0:1]
	ds_write_b64 v11, v[14:15] offset:4208
	v_add_u32_e32 v15, 4, v15
	v_add_u32_e32 v19, v10, v15
	ds_read_b32 v13, v19 offset:6144
	s_mov_b64 exec, -1
	s_waitcnt lgkmcnt(0)
; __device__ __forceinline__ void peer_score_unit(const Frame& F, int l, int unit) {
;     ...
;         for (int k = 0; k < 16; ++k) {
;             float best = c[0]; int bi = 0;
; #pragma unroll
;             for (int i = 1; i < 16; ++i) if (c[i] > best) { best = c[i]; bi = i; }
;             int pj = 0, lim = 16;
; #pragma unroll
;             for (int i = 0; i < 16; ++i) { pj = (i == bi) ? p[i] : pj; lim = (i == bi) ? 16 / (i + 1) : lim; }
;             fv[k] = best; fi[k] = bi * 16 + pj;
;             const int np = pj + 1; const float nb = bl[np & 15];
; #pragma unroll
;             for (int i = 0; i < 16; ++i) if (i == bi) { p[i] = np; c[i] = (np < lim) ? a[i] + nb : -INFINITY; }
;         }
;         float sum = 0.f;
;         const float fmx = fv[0];
; #pragma unroll
;         for (int k = 0; k < 16; ++k) { fv[k] = __expf(fv[k] - fmx); sum += fv[k]; }
;         const float inv = 1.0f / sum;
;         int* EID = (int*)(ws + WS_EID) + (size_t)(r0 + tid) * 128 + hd * 16; float* GW = (float*)(ws + WS_GW) + (size_t)(r0 + tid) * 128 + hd * 16;
; #pragma unroll
;         for (int k = 0; k < 16; ++k) { const int i1 = SI[tid * 16 + (fi[k] >> 4)], i2 = SI[(64 + tid) * 16 + (fi[k] & 15)]; EID[k] = i1 * 128 + i2; GW[k] = fv[k] * inv; }
	v_add_f32_e32 v6, v2, v3
	v_add_f32_e32 v16, v12, v13
	v_cmp_lt_u32_e32 vcc, v5, v7
	v_cmp_lt_u32_e64 s[10:11], v15, v7
	s_nop 0
	v_cndmask_b32_e32 v4, v0, v6, vcc
	v_cndmask_b32_e64 v14, v0, v16, s[10:11]
	s_nop 0
	v_max_f32_dpp v8, v4, v4 row_ror:8 row_mask:0xf bank_mask:0xf
	v_max_f32_dpp v18, v14, v14 row_ror:8 row_mask:0xf bank_mask:0xf
	s_nop 0
	v_max_f32_dpp v8, v8, v8 row_ror:4 row_mask:0xf bank_mask:0xf
	v_max_f32_dpp v18, v18, v18 row_ror:4 row_mask:0xf bank_mask:0xf
	s_nop 0
	v_max_f32_dpp v8, v8, v8 row_ror:2 row_mask:0xf bank_mask:0xf
	v_max_f32_dpp v18, v18, v18 row_ror:2 row_mask:0xf bank_mask:0xf
	s_nop 0
	v_max_f32_dpp v8, v8, v8 row_ror:1 row_mask:0xf bank_mask:0xf
	v_max_f32_dpp v18, v18, v18 row_ror:1 row_mask:0xf bank_mask:0xf
	v_cmp_eq_f32_e32 vcc, v4, v8
	v_cmp_eq_f32_e64 s[10:11], v14, v18
	s_sub_u32 s0, vcc_lo, s20
	s_subb_u32 s1, vcc_hi, s20
	s_andn2_b64 exec, vcc, s[0:1]
	ds_write_b64 v11, v[4:5] offset:120
	s_sub_u32 s0, s10, s20
	s_subb_u32 s1, s11, s20
	s_andn2_b64 exec, s[10:11], s[0:1]
	ds_write_b64 v11, v[14:15] offset:4216
	s_mov_b64 exec, -1
	ds_read_b64 v[2:3], v30
	ds_read_b64 v[12:13], v30 offset:4096
	v_lshrrev_b32_e32 v31, 4, v50
	v_lshlrev_b32_e32 v32, 2, v26
	v_lshl_add_u32 v31, v31, 9, v32
	v_add_u32_e32 v33, 0x4000, v31
	s_waitcnt lgkmcnt(0)
	v_lshrrev_b32_e32 v4, 8, v3
	v_and_b32_e32 v5, 0xff, v3
	v_lshl_add_u32 v4, v4, 2, v23
	v_add_u32_e32 v5, v23, v5
	ds_read_b32 v4, v4 offset:8192
	ds_read_b32 v5, v5 offset:12288
	v_sub_f32_e32 v2, v2, v24
	v_mul_f32_e32 v2, 0x3fb8aa3b, v2
	v_exp_f32_e32 v2, v2
	v_lshrrev_b32_e32 v14, 8, v13
	v_and_b32_e32 v15, 0xff, v13
	v_lshl_add_u32 v14, v14, 2, v23
	v_add_u32_e32 v15, v23, v15
	ds_read_b32 v14, v14 offset:10240
	ds_read_b32 v15, v15 offset:14336
	v_sub_f32_e32 v12, v12, v25
	v_mul_f32_e32 v12, 0x3fb8aa3b, v12
	v_exp_f32_e32 v12, v12
	s_nop 1
	v_add_f32_dpp v6, v2, v2 row_ror:8 row_mask:0xf bank_mask:0xf
	v_add_f32_dpp v16, v12, v12 row_ror:8 row_mask:0xf bank_mask:0xf
	s_nop 0
	v_add_f32_dpp v6, v6, v6 row_ror:4 row_mask:0xf bank_mask:0xf
	v_add_f32_dpp v16, v16, v16 row_ror:4 row_mask:0xf bank_mask:0xf
	s_nop 0
	v_add_f32_dpp v6, v6, v6 row_ror:2 row_mask:0xf bank_mask:0xf
	v_add_f32_dpp v16, v16, v16 row_ror:2 row_mask:0xf bank_mask:0xf
	s_nop 0
	v_add_f32_dpp v6, v6, v6 row_ror:1 row_mask:0xf bank_mask:0xf
	v_add_f32_dpp v16, v16, v16 row_ror:1 row_mask:0xf bank_mask:0xf
	v_div_scale_f32 v34, s[0:1], v6, v6, 1.0
	v_rcp_f32_e32 v35, v34
	s_nop 0
	v_fma_f32 v36, -v34, v35, 1.0
	v_fmac_f32_e32 v35, v36, v35
	v_div_scale_f32 v36, vcc, 1.0, v6, 1.0
	v_mul_f32_e32 v37, v36, v35
	v_fma_f32 v38, -v34, v37, v36
	v_fmac_f32_e32 v37, v38, v35
	v_fma_f32 v34, -v34, v37, v36
	v_div_fmas_f32 v34, v34, v35, v37
	v_div_fixup_f32 v34, v34, v6, 1.0
	v_div_scale_f32 v40, s[0:1], v16, v16, 1.0
	v_rcp_f32_e32 v41, v40
	s_nop 0
	v_fma_f32 v42, -v40, v41, 1.0
	v_fmac_f32_e32 v41, v42, v41
	v_div_scale_f32 v42, vcc, 1.0, v16, 1.0
	v_mul_f32_e32 v43, v42, v41
	v_fma_f32 v44, -v40, v43, v42
	v_fmac_f32_e32 v43, v44, v41
	v_fma_f32 v40, -v40, v43, v42
	v_div_fmas_f32 v40, v40, v41, v43
	v_div_fixup_f32 v40, v40, v16, 1.0
	v_mul_f32_e32 v2, v2, v34
	v_mul_f32_e32 v12, v12, v40
	s_waitcnt lgkmcnt(0)
	v_lshl_add_u32 v4, v4, 7, v5
	v_lshl_add_u32 v14, v14, 7, v15
	global_store_dword v31, v4, s[8:9]
	global_store_dword v31, v2, s[14:15]
	global_store_dword v33, v14, s[8:9]
	global_store_dword v33, v12, s[14:15]
